# attn_cmp: top-16 block selection via 32-step ballot binary search on order-preserving integer keys (replaces 64-step ds_bpermute rank loop; identical selection set) + scan DPP cumsum + posbias batchin
# speedup vs baseline: 1.0075x; 1.0075x over previous
; __device__ __forceinline__ void nsa_attn_cmp(const Ctx& c, const bf16* Q, const bf16* KCb, const bf16* VCT, const float* Gt, float* NACC, unsigned long long* SMg) {
;     ...
;             const bool forced = (lane == 0) || (lane <= qb && lane > qb - 3), future = lane > qb;
;             const float score = forced ? 1e30f : (future ? -1e30f : imp); int rank = 0;
;             for (int k = 0; k < 64; ++k) { const float sk = __shfl(score, k); rank += (sk > score || (sk == score && k < lane)) ? 1 : 0; }
;             const unsigned long long sel = __ballot(rank < 16); if (lane == 0) SMg[(size_t)bg * SEQ + t0 + tl] = sel; }
.LBB0_2190:
	s_or_b64 exec, exec, s[8:9]
	s_add_i32 s8, s41, -3
	v_cmp_ge_i32_e64 s[6:7], s41, v164
	v_cmp_lt_i32_e64 s[8:9], s8, v164
	s_and_b64 s[8:9], s[6:7], s[8:9]
	v_cmp_lt_i32_e64 s[6:7], s41, v164
	s_or_b64 s[8:9], s[2:3], s[8:9]
	s_mov_b32 s28, 0
	v_cndmask_b32_e64 v5, v5, v226, s[6:7]
	v_cndmask_b32_e64 v5, v5, v227, s[8:9]
	v_ashrrev_i32_e32 v6, 31, v5
	v_or_b32_e32 v6, 0x80000000, v6
	v_xor_b32_e32 v6, v5, v6
	s_mov_b32 s28, 0
	s_or_b32 s10, s28, 0x80000000
	v_cmp_ge_u32_e64 s[12:13], v6, s10
	s_bcnt1_i32_b64 s11, s[12:13]
	s_cmp_ge_u32 s11, 16
	s_cselect_b32 s28, s10, s28
	s_or_b32 s10, s28, 0x40000000
	v_cmp_ge_u32_e64 s[12:13], v6, s10
	s_bcnt1_i32_b64 s11, s[12:13]
	s_cmp_ge_u32 s11, 16
	s_cselect_b32 s28, s10, s28
	s_or_b32 s10, s28, 0x20000000
	v_cmp_ge_u32_e64 s[12:13], v6, s10
	s_bcnt1_i32_b64 s11, s[12:13]
	s_cmp_ge_u32 s11, 16
	s_cselect_b32 s28, s10, s28
	s_or_b32 s10, s28, 0x10000000
	v_cmp_ge_u32_e64 s[12:13], v6, s10
	s_bcnt1_i32_b64 s11, s[12:13]
	s_cmp_ge_u32 s11, 16
	s_cselect_b32 s28, s10, s28
	s_or_b32 s10, s28, 0x8000000
	v_cmp_ge_u32_e64 s[12:13], v6, s10
	s_bcnt1_i32_b64 s11, s[12:13]
	s_cmp_ge_u32 s11, 16
	s_cselect_b32 s28, s10, s28
	s_or_b32 s10, s28, 0x4000000
	v_cmp_ge_u32_e64 s[12:13], v6, s10
	s_bcnt1_i32_b64 s11, s[12:13]
	s_cmp_ge_u32 s11, 16
	s_cselect_b32 s28, s10, s28
	s_or_b32 s10, s28, 0x2000000
	v_cmp_ge_u32_e64 s[12:13], v6, s10
	s_bcnt1_i32_b64 s11, s[12:13]
	s_cmp_ge_u32 s11, 16
	s_cselect_b32 s28, s10, s28
	s_or_b32 s10, s28, 0x1000000
	v_cmp_ge_u32_e64 s[12:13], v6, s10
	s_bcnt1_i32_b64 s11, s[12:13]
	s_cmp_ge_u32 s11, 16
	s_cselect_b32 s28, s10, s28
	s_or_b32 s10, s28, 0x800000
	v_cmp_ge_u32_e64 s[12:13], v6, s10
	s_bcnt1_i32_b64 s11, s[12:13]
	s_cmp_ge_u32 s11, 16
	s_cselect_b32 s28, s10, s28
	s_or_b32 s10, s28, 0x400000
	v_cmp_ge_u32_e64 s[12:13], v6, s10
	s_bcnt1_i32_b64 s11, s[12:13]
	s_cmp_ge_u32 s11, 16
	s_cselect_b32 s28, s10, s28
	s_or_b32 s10, s28, 0x200000
	v_cmp_ge_u32_e64 s[12:13], v6, s10
	s_bcnt1_i32_b64 s11, s[12:13]
	s_cmp_ge_u32 s11, 16
	s_cselect_b32 s28, s10, s28
	s_or_b32 s10, s28, 0x100000
	v_cmp_ge_u32_e64 s[12:13], v6, s10
	s_bcnt1_i32_b64 s11, s[12:13]
	s_cmp_ge_u32 s11, 16
	s_cselect_b32 s28, s10, s28
	s_or_b32 s10, s28, 0x80000
	v_cmp_ge_u32_e64 s[12:13], v6, s10
	s_bcnt1_i32_b64 s11, s[12:13]
	s_cmp_ge_u32 s11, 16
	s_cselect_b32 s28, s10, s28
	s_or_b32 s10, s28, 0x40000
	v_cmp_ge_u32_e64 s[12:13], v6, s10
	s_bcnt1_i32_b64 s11, s[12:13]
	s_cmp_ge_u32 s11, 16
	s_cselect_b32 s28, s10, s28
	s_or_b32 s10, s28, 0x20000
	v_cmp_ge_u32_e64 s[12:13], v6, s10
	s_bcnt1_i32_b64 s11, s[12:13]
	s_cmp_ge_u32 s11, 16
	s_cselect_b32 s28, s10, s28
	s_or_b32 s10, s28, 0x10000
	v_cmp_ge_u32_e64 s[12:13], v6, s10
	s_bcnt1_i32_b64 s11, s[12:13]
	s_cmp_ge_u32 s11, 16
	s_cselect_b32 s28, s10, s28
	s_or_b32 s10, s28, 0x8000
	v_cmp_ge_u32_e64 s[12:13], v6, s10
	s_bcnt1_i32_b64 s11, s[12:13]
	s_cmp_ge_u32 s11, 16
	s_cselect_b32 s28, s10, s28
	s_or_b32 s10, s28, 0x4000
	v_cmp_ge_u32_e64 s[12:13], v6, s10
	s_bcnt1_i32_b64 s11, s[12:13]
	s_cmp_ge_u32 s11, 16
	s_cselect_b32 s28, s10, s28
	s_or_b32 s10, s28, 0x2000
	v_cmp_ge_u32_e64 s[12:13], v6, s10
	s_bcnt1_i32_b64 s11, s[12:13]
	s_cmp_ge_u32 s11, 16
	s_cselect_b32 s28, s10, s28
	s_or_b32 s10, s28, 0x1000
	v_cmp_ge_u32_e64 s[12:13], v6, s10
	s_bcnt1_i32_b64 s11, s[12:13]
	s_cmp_ge_u32 s11, 16
	s_cselect_b32 s28, s10, s28
	s_or_b32 s10, s28, 0x800
	v_cmp_ge_u32_e64 s[12:13], v6, s10
	s_bcnt1_i32_b64 s11, s[12:13]
	s_cmp_ge_u32 s11, 16
	s_cselect_b32 s28, s10, s28
	s_or_b32 s10, s28, 0x400
	v_cmp_ge_u32_e64 s[12:13], v6, s10
	s_bcnt1_i32_b64 s11, s[12:13]
	s_cmp_ge_u32 s11, 16
	s_cselect_b32 s28, s10, s28
	s_or_b32 s10, s28, 0x200
	v_cmp_ge_u32_e64 s[12:13], v6, s10
	s_bcnt1_i32_b64 s11, s[12:13]
	s_cmp_ge_u32 s11, 16
	s_cselect_b32 s28, s10, s28
	s_or_b32 s10, s28, 0x100
	v_cmp_ge_u32_e64 s[12:13], v6, s10
	s_bcnt1_i32_b64 s11, s[12:13]
	s_cmp_ge_u32 s11, 16
	s_cselect_b32 s28, s10, s28
	s_or_b32 s10, s28, 0x80
	v_cmp_ge_u32_e64 s[12:13], v6, s10
	s_bcnt1_i32_b64 s11, s[12:13]
	s_cmp_ge_u32 s11, 16
	s_cselect_b32 s28, s10, s28
	s_or_b32 s10, s28, 0x40
	v_cmp_ge_u32_e64 s[12:13], v6, s10
	s_bcnt1_i32_b64 s11, s[12:13]
	s_cmp_ge_u32 s11, 16
	s_cselect_b32 s28, s10, s28
	s_or_b32 s10, s28, 0x20
	v_cmp_ge_u32_e64 s[12:13], v6, s10
	s_bcnt1_i32_b64 s11, s[12:13]
	s_cmp_ge_u32 s11, 16
	s_cselect_b32 s28, s10, s28
	s_or_b32 s10, s28, 0x10
	v_cmp_ge_u32_e64 s[12:13], v6, s10
	s_bcnt1_i32_b64 s11, s[12:13]
	s_cmp_ge_u32 s11, 16
	s_cselect_b32 s28, s10, s28
	s_or_b32 s10, s28, 0x8
	v_cmp_ge_u32_e64 s[12:13], v6, s10
	s_bcnt1_i32_b64 s11, s[12:13]
	s_cmp_ge_u32 s11, 16
	s_cselect_b32 s28, s10, s28
	s_or_b32 s10, s28, 0x4
	v_cmp_ge_u32_e64 s[12:13], v6, s10
	s_bcnt1_i32_b64 s11, s[12:13]
	s_cmp_ge_u32 s11, 16
	s_cselect_b32 s28, s10, s28
	s_or_b32 s10, s28, 0x2
	v_cmp_ge_u32_e64 s[12:13], v6, s10
	s_bcnt1_i32_b64 s11, s[12:13]
	s_cmp_ge_u32 s11, 16
	s_cselect_b32 s28, s10, s28
	s_or_b32 s10, s28, 0x1
	v_cmp_ge_u32_e64 s[12:13], v6, s10
	s_bcnt1_i32_b64 s11, s[12:13]
	s_cmp_ge_u32 s11, 16
	s_cselect_b32 s28, s10, s28
	v_cmp_gt_u32_e64 s[12:13], v6, s28
	v_cmp_eq_u32_e64 s[14:15], v6, s28
	s_bcnt1_i32_b64 s11, s[12:13]
	s_sub_u32 s11, 16, s11
	v_mbcnt_lo_u32_b32 v7, s14, 0
	v_mbcnt_hi_u32_b32 v7, s15, v7
	v_cmp_gt_u32_e64 s[10:11], s11, v7
	s_and_b64 s[14:15], s[14:15], s[10:11]
	s_or_b64 s[14:15], s[12:13], s[14:15]
.LBB0_2191:
	s_lshl_b32 s10, s35, 15
	s_add_u32 s12, s54, s10
	s_mov_b32 s35, s29
	s_addc_u32 s13, s55, 0
	s_lshl_b64 s[10:11], s[34:35], 3
	s_add_u32 s34, s12, s10
	s_addc_u32 s35, s13, s11
	s_mov_b64 s[12:13], s[14:15]
	s_and_saveexec_b64 s[10:11], s[2:3]
	s_cbranch_execz .LBB0_2194
	s_lshl_b32 s14, s31, 3
	v_mov_b32_e32 v5, s14
	v_mov_b64_e32 v[6:7], s[12:13]
	global_store_dwordx2 v5, v[6:7], s[34:35]

; __device__ __forceinline__ void nsa_attn_cmp(const Ctx& c, const bf16* Q, const bf16* KCb, const bf16* VCT, const float* Gt, float* NACC, unsigned long long* SMg) {
;     ...
;             const bool forced = (lane == 0) || (lane <= qb && lane > qb - 3), future = lane > qb;
;             const float score = forced ? 1e30f : (future ? -1e30f : imp); int rank = 0;
;             for (int k = 0; k < 64; ++k) { const float sk = __shfl(score, k); rank += (sk > score || (sk == score && k < lane)) ? 1 : 0; }
;             const unsigned long long sel = __ballot(rank < 16); if (lane == 0) SMg[(size_t)bg * SEQ + t0 + tl] = sel; }
.LBB0_2198:
	s_or_b64 exec, exec, s[12:13]
	v_cndmask_b32_e64 v5, v5, v226, s[6:7]
	v_cndmask_b32_e64 v5, v5, v227, s[8:9]
	s_mov_b32 s28, 0
	v_ashrrev_i32_e32 v6, 31, v5
	v_or_b32_e32 v6, 0x80000000, v6
	v_xor_b32_e32 v6, v5, v6
	s_mov_b32 s28, 0
	s_or_b32 s10, s28, 0x80000000
	v_cmp_ge_u32_e64 s[12:13], v6, s10
	s_bcnt1_i32_b64 s11, s[12:13]
	s_cmp_ge_u32 s11, 16
	s_cselect_b32 s28, s10, s28
	s_or_b32 s10, s28, 0x40000000
	v_cmp_ge_u32_e64 s[12:13], v6, s10
	s_bcnt1_i32_b64 s11, s[12:13]
	s_cmp_ge_u32 s11, 16
	s_cselect_b32 s28, s10, s28
	s_or_b32 s10, s28, 0x20000000
	v_cmp_ge_u32_e64 s[12:13], v6, s10
	s_bcnt1_i32_b64 s11, s[12:13]
	s_cmp_ge_u32 s11, 16
	s_cselect_b32 s28, s10, s28
	s_or_b32 s10, s28, 0x10000000
	v_cmp_ge_u32_e64 s[12:13], v6, s10
	s_bcnt1_i32_b64 s11, s[12:13]
	s_cmp_ge_u32 s11, 16
	s_cselect_b32 s28, s10, s28
	s_or_b32 s10, s28, 0x8000000
	v_cmp_ge_u32_e64 s[12:13], v6, s10
	s_bcnt1_i32_b64 s11, s[12:13]
	s_cmp_ge_u32 s11, 16
	s_cselect_b32 s28, s10, s28
	s_or_b32 s10, s28, 0x4000000
	v_cmp_ge_u32_e64 s[12:13], v6, s10
	s_bcnt1_i32_b64 s11, s[12:13]
	s_cmp_ge_u32 s11, 16
	s_cselect_b32 s28, s10, s28
	s_or_b32 s10, s28, 0x2000000
	v_cmp_ge_u32_e64 s[12:13], v6, s10
	s_bcnt1_i32_b64 s11, s[12:13]
	s_cmp_ge_u32 s11, 16
	s_cselect_b32 s28, s10, s28
	s_or_b32 s10, s28, 0x1000000
	v_cmp_ge_u32_e64 s[12:13], v6, s10
	s_bcnt1_i32_b64 s11, s[12:13]
	s_cmp_ge_u32 s11, 16
	s_cselect_b32 s28, s10, s28
	s_or_b32 s10, s28, 0x800000
	v_cmp_ge_u32_e64 s[12:13], v6, s10
	s_bcnt1_i32_b64 s11, s[12:13]
	s_cmp_ge_u32 s11, 16
	s_cselect_b32 s28, s10, s28
	s_or_b32 s10, s28, 0x400000
	v_cmp_ge_u32_e64 s[12:13], v6, s10
	s_bcnt1_i32_b64 s11, s[12:13]
	s_cmp_ge_u32 s11, 16
	s_cselect_b32 s28, s10, s28
	s_or_b32 s10, s28, 0x200000
	v_cmp_ge_u32_e64 s[12:13], v6, s10
	s_bcnt1_i32_b64 s11, s[12:13]
	s_cmp_ge_u32 s11, 16
	s_cselect_b32 s28, s10, s28
	s_or_b32 s10, s28, 0x100000
	v_cmp_ge_u32_e64 s[12:13], v6, s10
	s_bcnt1_i32_b64 s11, s[12:13]
	s_cmp_ge_u32 s11, 16
	s_cselect_b32 s28, s10, s28
	s_or_b32 s10, s28, 0x80000
	v_cmp_ge_u32_e64 s[12:13], v6, s10
	s_bcnt1_i32_b64 s11, s[12:13]
	s_cmp_ge_u32 s11, 16
	s_cselect_b32 s28, s10, s28
	s_or_b32 s10, s28, 0x40000
	v_cmp_ge_u32_e64 s[12:13], v6, s10
	s_bcnt1_i32_b64 s11, s[12:13]
	s_cmp_ge_u32 s11, 16
	s_cselect_b32 s28, s10, s28
	s_or_b32 s10, s28, 0x20000
	v_cmp_ge_u32_e64 s[12:13], v6, s10
	s_bcnt1_i32_b64 s11, s[12:13]
	s_cmp_ge_u32 s11, 16
	s_cselect_b32 s28, s10, s28
	s_or_b32 s10, s28, 0x10000
	v_cmp_ge_u32_e64 s[12:13], v6, s10
	s_bcnt1_i32_b64 s11, s[12:13]
	s_cmp_ge_u32 s11, 16
	s_cselect_b32 s28, s10, s28
	s_or_b32 s10, s28, 0x8000
	v_cmp_ge_u32_e64 s[12:13], v6, s10
	s_bcnt1_i32_b64 s11, s[12:13]
	s_cmp_ge_u32 s11, 16
	s_cselect_b32 s28, s10, s28
	s_or_b32 s10, s28, 0x4000
	v_cmp_ge_u32_e64 s[12:13], v6, s10
	s_bcnt1_i32_b64 s11, s[12:13]
	s_cmp_ge_u32 s11, 16
	s_cselect_b32 s28, s10, s28
	s_or_b32 s10, s28, 0x2000
	v_cmp_ge_u32_e64 s[12:13], v6, s10
	s_bcnt1_i32_b64 s11, s[12:13]
	s_cmp_ge_u32 s11, 16
	s_cselect_b32 s28, s10, s28
	s_or_b32 s10, s28, 0x1000
	v_cmp_ge_u32_e64 s[12:13], v6, s10
	s_bcnt1_i32_b64 s11, s[12:13]
	s_cmp_ge_u32 s11, 16
	s_cselect_b32 s28, s10, s28
	s_or_b32 s10, s28, 0x800
	v_cmp_ge_u32_e64 s[12:13], v6, s10
	s_bcnt1_i32_b64 s11, s[12:13]
	s_cmp_ge_u32 s11, 16
	s_cselect_b32 s28, s10, s28
	s_or_b32 s10, s28, 0x400
	v_cmp_ge_u32_e64 s[12:13], v6, s10
	s_bcnt1_i32_b64 s11, s[12:13]
	s_cmp_ge_u32 s11, 16
	s_cselect_b32 s28, s10, s28
	s_or_b32 s10, s28, 0x200
	v_cmp_ge_u32_e64 s[12:13], v6, s10
	s_bcnt1_i32_b64 s11, s[12:13]
	s_cmp_ge_u32 s11, 16
	s_cselect_b32 s28, s10, s28
	s_or_b32 s10, s28, 0x100
	v_cmp_ge_u32_e64 s[12:13], v6, s10
	s_bcnt1_i32_b64 s11, s[12:13]
	s_cmp_ge_u32 s11, 16
	s_cselect_b32 s28, s10, s28
	s_or_b32 s10, s28, 0x80
	v_cmp_ge_u32_e64 s[12:13], v6, s10
	s_bcnt1_i32_b64 s11, s[12:13]
	s_cmp_ge_u32 s11, 16
	s_cselect_b32 s28, s10, s28
	s_or_b32 s10, s28, 0x40
	v_cmp_ge_u32_e64 s[12:13], v6, s10
	s_bcnt1_i32_b64 s11, s[12:13]
	s_cmp_ge_u32 s11, 16
	s_cselect_b32 s28, s10, s28
	s_or_b32 s10, s28, 0x20
	v_cmp_ge_u32_e64 s[12:13], v6, s10
	s_bcnt1_i32_b64 s11, s[12:13]
	s_cmp_ge_u32 s11, 16
	s_cselect_b32 s28, s10, s28
	s_or_b32 s10, s28, 0x10
	v_cmp_ge_u32_e64 s[12:13], v6, s10
	s_bcnt1_i32_b64 s11, s[12:13]
	s_cmp_ge_u32 s11, 16
	s_cselect_b32 s28, s10, s28
	s_or_b32 s10, s28, 0x8
	v_cmp_ge_u32_e64 s[12:13], v6, s10
	s_bcnt1_i32_b64 s11, s[12:13]
	s_cmp_ge_u32 s11, 16
	s_cselect_b32 s28, s10, s28
	s_or_b32 s10, s28, 0x4
	v_cmp_ge_u32_e64 s[12:13], v6, s10
	s_bcnt1_i32_b64 s11, s[12:13]
	s_cmp_ge_u32 s11, 16
	s_cselect_b32 s28, s10, s28
	s_or_b32 s10, s28, 0x2
	v_cmp_ge_u32_e64 s[12:13], v6, s10
	s_bcnt1_i32_b64 s11, s[12:13]
	s_cmp_ge_u32 s11, 16
	s_cselect_b32 s28, s10, s28
	s_or_b32 s10, s28, 0x1
	v_cmp_ge_u32_e64 s[12:13], v6, s10
	s_bcnt1_i32_b64 s11, s[12:13]
	s_cmp_ge_u32 s11, 16
	s_cselect_b32 s28, s10, s28
	v_cmp_gt_u32_e64 s[12:13], v6, s28
	v_cmp_eq_u32_e64 s[14:15], v6, s28
	s_bcnt1_i32_b64 s11, s[12:13]
	s_sub_u32 s11, 16, s11
	v_mbcnt_lo_u32_b32 v7, s14, 0
	v_mbcnt_hi_u32_b32 v7, s15, v7
	v_cmp_gt_u32_e64 s[10:11], s11, v7
	s_and_b64 s[14:15], s[14:15], s[10:11]
	s_or_b64 s[14:15], s[12:13], s[14:15]
.LBB0_2199:
	s_mov_b64 s[12:13], s[14:15]
	s_and_saveexec_b64 s[10:11], s[2:3]
	s_cbranch_execz .LBB0_2202
	s_lshl_b32 s14, s31, 3
	v_mov_b32_e32 v5, s14
	v_mov_b64_e32 v[6:7], s[12:13]
	global_store_dwordx2 v5, v[6:7], s[34:35] offset:8

; __device__ __forceinline__ void nsa_attn_cmp(const Ctx& c, const bf16* Q, const bf16* KCb, const bf16* VCT, const float* Gt, float* NACC, unsigned long long* SMg) {
;     ...
;             for (int k = 0; k < 64; ++k) { const float sk = __shfl(score, k); rank += (sk > score || (sk == score && k < lane)) ? 1 : 0; }
;             const unsigned long long sel = __ballot(rank < 16); if (lane == 0) SMg[(size_t)bg * SEQ + t0 + tl] = sel; }
.LBB0_2207:
	s_mov_b64 s[12:13], s[14:15]
	s_and_saveexec_b64 s[10:11], s[2:3]
	s_cbranch_execz .LBB0_2210
	s_lshl_b32 s14, s31, 3
	v_mov_b32_e32 v5, s14
	v_mov_b64_e32 v[6:7], s[12:13]
	global_store_dwordx2 v5, v[6:7], s[34:35] offset:16

; __device__ __forceinline__ void nsa_attn_cmp(const Ctx& c, const bf16* Q, const bf16* KCb, const bf16* VCT, const float* Gt, float* NACC, unsigned long long* SMg) {
;     ...
;             for (int k = 0; k < 64; ++k) { const float sk = __shfl(score, k); rank += (sk > score || (sk == score && k < lane)) ? 1 : 0; }
;             const unsigned long long sel = __ballot(rank < 16); if (lane == 0) SMg[(size_t)bg * SEQ + t0 + tl] = sel; }
.LBB0_2215:
	s_mov_b64 s[12:13], s[14:15]
	s_and_saveexec_b64 s[10:11], s[2:3]
	s_cbranch_execz .LBB0_2218
	s_lshl_b32 s14, s31, 3
	v_mov_b32_e32 v5, s14
	v_mov_b64_e32 v[6:7], s[12:13]
	global_store_dwordx2 v5, v[6:7], s[34:35] offset:24

; __device__ __forceinline__ void nsa_attn_cmp(const Ctx& c, const bf16* Q, const bf16* KCb, const bf16* VCT, const float* Gt, float* NACC, unsigned long long* SMg) {
;     ...
;             for (int k = 0; k < 64; ++k) { const float sk = __shfl(score, k); rank += (sk > score || (sk == score && k < lane)) ? 1 : 0; }
;             const unsigned long long sel = __ballot(rank < 16); if (lane == 0) SMg[(size_t)bg * SEQ + t0 + tl] = sel; }
.LBB0_2223:
	s_mov_b64 s[12:13], s[14:15]
	s_and_saveexec_b64 s[10:11], s[2:3]
	s_cbranch_execz .LBB0_2226
	s_lshl_b32 s14, s31, 3
	v_mov_b32_e32 v5, s14
	v_mov_b64_e32 v[6:7], s[12:13]
	global_store_dwordx2 v5, v[6:7], s[34:35] offset:32

; __device__ __forceinline__ void nsa_attn_cmp(const Ctx& c, const bf16* Q, const bf16* KCb, const bf16* VCT, const float* Gt, float* NACC, unsigned long long* SMg) {
;     ...
;             for (int k = 0; k < 64; ++k) { const float sk = __shfl(score, k); rank += (sk > score || (sk == score && k < lane)) ? 1 : 0; }
;             const unsigned long long sel = __ballot(rank < 16); if (lane == 0) SMg[(size_t)bg * SEQ + t0 + tl] = sel; }
.LBB0_2231:
	s_mov_b64 s[12:13], s[14:15]
	s_and_saveexec_b64 s[10:11], s[2:3]
	s_cbranch_execz .LBB0_2234
	s_lshl_b32 s14, s31, 3
	v_mov_b32_e32 v5, s14
	v_mov_b64_e32 v[6:7], s[12:13]
	global_store_dwordx2 v5, v[6:7], s[34:35] offset:40

; __device__ __forceinline__ void nsa_attn_cmp(const Ctx& c, const bf16* Q, const bf16* KCb, const bf16* VCT, const float* Gt, float* NACC, unsigned long long* SMg) {
;     ...
;             for (int k = 0; k < 64; ++k) { const float sk = __shfl(score, k); rank += (sk > score || (sk == score && k < lane)) ? 1 : 0; }
;             const unsigned long long sel = __ballot(rank < 16); if (lane == 0) SMg[(size_t)bg * SEQ + t0 + tl] = sel; }
.LBB0_2239:
	s_mov_b64 s[12:13], s[14:15]
	s_and_saveexec_b64 s[10:11], s[2:3]
	s_cbranch_execz .LBB0_2242
	s_lshl_b32 s14, s31, 3
	v_mov_b32_e32 v5, s14
	v_mov_b64_e32 v[6:7], s[12:13]
	global_store_dwordx2 v5, v[6:7], s[34:35] offset:48

; #define LAS __attribute__((address_space(3)))
; __device__ __forceinline__ void nsa_attn_cmp(const Ctx& c, const bf16* Q, const bf16* KCb, const bf16* VCT, const float* Gt, float* NACC, unsigned long long* SMg) {
;     ...
;         for (int i = 0; i < 8; ++i) { const int tl = 8 * c.wave + i; const LAS float* pr = PS + tl * fa::PS_STRIDE; float imp = 0.f;
;             { const int i0 = (4 * lane - 1) < 0 ? 0 : 4 * lane - 1; int i1 = (4 * lane + 3) > 254 ? 254 : 4 * lane + 3; if (i1 > 64 * ntile - 1) i1 = 64 * ntile - 1; for (int q = i0; q <= i1; ++q) imp += pr[q]; }
;             const bool forced = (lane == 0) || (lane <= qb && lane > qb - 3), future = lane > qb;
;             const float score = forced ? 1e30f : (future ? -1e30f : imp); int rank = 0;
;             for (int k = 0; k < 64; ++k) { const float sk = __shfl(score, k); rank += (sk > score || (sk == score && k < lane)) ? 1 : 0; }
;             const unsigned long long sel = __ballot(rank < 16); if (lane == 0) SMg[(size_t)bg * SEQ + t0 + tl] = sel; }
.LBB0_2246:
	s_or_b64 exec, exec, s[10:11]
	v_cndmask_b32_e64 v4, v5, v226, s[6:7]
	v_cndmask_b32_e64 v4, v4, v227, s[8:9]
	s_mov_b32 s10, 0
	v_ashrrev_i32_e32 v5, 31, v4
	v_or_b32_e32 v5, 0x80000000, v5
	v_xor_b32_e32 v5, v4, v5
	s_mov_b32 s10, 0
	s_or_b32 s6, s10, 0x80000000
	v_cmp_ge_u32_e64 s[8:9], v5, s6
	s_bcnt1_i32_b64 s7, s[8:9]
	s_cmp_ge_u32 s7, 16
	s_cselect_b32 s10, s6, s10
	s_or_b32 s6, s10, 0x40000000
	v_cmp_ge_u32_e64 s[8:9], v5, s6
	s_bcnt1_i32_b64 s7, s[8:9]
	s_cmp_ge_u32 s7, 16
	s_cselect_b32 s10, s6, s10
	s_or_b32 s6, s10, 0x20000000
	v_cmp_ge_u32_e64 s[8:9], v5, s6
	s_bcnt1_i32_b64 s7, s[8:9]
	s_cmp_ge_u32 s7, 16
	s_cselect_b32 s10, s6, s10
	s_or_b32 s6, s10, 0x10000000
	v_cmp_ge_u32_e64 s[8:9], v5, s6
	s_bcnt1_i32_b64 s7, s[8:9]
	s_cmp_ge_u32 s7, 16
	s_cselect_b32 s10, s6, s10
	s_or_b32 s6, s10, 0x8000000
	v_cmp_ge_u32_e64 s[8:9], v5, s6
	s_bcnt1_i32_b64 s7, s[8:9]
	s_cmp_ge_u32 s7, 16
	s_cselect_b32 s10, s6, s10
	s_or_b32 s6, s10, 0x4000000
	v_cmp_ge_u32_e64 s[8:9], v5, s6
	s_bcnt1_i32_b64 s7, s[8:9]
	s_cmp_ge_u32 s7, 16
	s_cselect_b32 s10, s6, s10
	s_or_b32 s6, s10, 0x2000000
	v_cmp_ge_u32_e64 s[8:9], v5, s6
	s_bcnt1_i32_b64 s7, s[8:9]
	s_cmp_ge_u32 s7, 16
	s_cselect_b32 s10, s6, s10
	s_or_b32 s6, s10, 0x1000000
	v_cmp_ge_u32_e64 s[8:9], v5, s6
	s_bcnt1_i32_b64 s7, s[8:9]
	s_cmp_ge_u32 s7, 16
	s_cselect_b32 s10, s6, s10
	s_or_b32 s6, s10, 0x800000
	v_cmp_ge_u32_e64 s[8:9], v5, s6
	s_bcnt1_i32_b64 s7, s[8:9]
	s_cmp_ge_u32 s7, 16
	s_cselect_b32 s10, s6, s10
	s_or_b32 s6, s10, 0x400000
	v_cmp_ge_u32_e64 s[8:9], v5, s6
	s_bcnt1_i32_b64 s7, s[8:9]
	s_cmp_ge_u32 s7, 16
	s_cselect_b32 s10, s6, s10
	s_or_b32 s6, s10, 0x200000
	v_cmp_ge_u32_e64 s[8:9], v5, s6
	s_bcnt1_i32_b64 s7, s[8:9]
	s_cmp_ge_u32 s7, 16
	s_cselect_b32 s10, s6, s10
	s_or_b32 s6, s10, 0x100000
	v_cmp_ge_u32_e64 s[8:9], v5, s6
	s_bcnt1_i32_b64 s7, s[8:9]
	s_cmp_ge_u32 s7, 16
	s_cselect_b32 s10, s6, s10
	s_or_b32 s6, s10, 0x80000
	v_cmp_ge_u32_e64 s[8:9], v5, s6
	s_bcnt1_i32_b64 s7, s[8:9]
	s_cmp_ge_u32 s7, 16
	s_cselect_b32 s10, s6, s10
	s_or_b32 s6, s10, 0x40000
	v_cmp_ge_u32_e64 s[8:9], v5, s6
	s_bcnt1_i32_b64 s7, s[8:9]
	s_cmp_ge_u32 s7, 16
	s_cselect_b32 s10, s6, s10
	s_or_b32 s6, s10, 0x20000
	v_cmp_ge_u32_e64 s[8:9], v5, s6
	s_bcnt1_i32_b64 s7, s[8:9]
	s_cmp_ge_u32 s7, 16
	s_cselect_b32 s10, s6, s10
	s_or_b32 s6, s10, 0x10000
	v_cmp_ge_u32_e64 s[8:9], v5, s6
	s_bcnt1_i32_b64 s7, s[8:9]
	s_cmp_ge_u32 s7, 16
	s_cselect_b32 s10, s6, s10
	s_or_b32 s6, s10, 0x8000
	v_cmp_ge_u32_e64 s[8:9], v5, s6
	s_bcnt1_i32_b64 s7, s[8:9]
	s_cmp_ge_u32 s7, 16
	s_cselect_b32 s10, s6, s10
	s_or_b32 s6, s10, 0x4000
	v_cmp_ge_u32_e64 s[8:9], v5, s6
	s_bcnt1_i32_b64 s7, s[8:9]
	s_cmp_ge_u32 s7, 16
	s_cselect_b32 s10, s6, s10
	s_or_b32 s6, s10, 0x2000
	v_cmp_ge_u32_e64 s[8:9], v5, s6
	s_bcnt1_i32_b64 s7, s[8:9]
	s_cmp_ge_u32 s7, 16
	s_cselect_b32 s10, s6, s10
	s_or_b32 s6, s10, 0x1000
	v_cmp_ge_u32_e64 s[8:9], v5, s6
	s_bcnt1_i32_b64 s7, s[8:9]
	s_cmp_ge_u32 s7, 16
	s_cselect_b32 s10, s6, s10
	s_or_b32 s6, s10, 0x800
	v_cmp_ge_u32_e64 s[8:9], v5, s6
	s_bcnt1_i32_b64 s7, s[8:9]
	s_cmp_ge_u32 s7, 16
	s_cselect_b32 s10, s6, s10
	s_or_b32 s6, s10, 0x400
	v_cmp_ge_u32_e64 s[8:9], v5, s6
	s_bcnt1_i32_b64 s7, s[8:9]
	s_cmp_ge_u32 s7, 16
	s_cselect_b32 s10, s6, s10
	s_or_b32 s6, s10, 0x200
	v_cmp_ge_u32_e64 s[8:9], v5, s6
	s_bcnt1_i32_b64 s7, s[8:9]
	s_cmp_ge_u32 s7, 16
	s_cselect_b32 s10, s6, s10
	s_or_b32 s6, s10, 0x100
	v_cmp_ge_u32_e64 s[8:9], v5, s6
	s_bcnt1_i32_b64 s7, s[8:9]
	s_cmp_ge_u32 s7, 16
	s_cselect_b32 s10, s6, s10
	s_or_b32 s6, s10, 0x80
	v_cmp_ge_u32_e64 s[8:9], v5, s6
	s_bcnt1_i32_b64 s7, s[8:9]
	s_cmp_ge_u32 s7, 16
	s_cselect_b32 s10, s6, s10
	s_or_b32 s6, s10, 0x40
	v_cmp_ge_u32_e64 s[8:9], v5, s6
	s_bcnt1_i32_b64 s7, s[8:9]
	s_cmp_ge_u32 s7, 16
	s_cselect_b32 s10, s6, s10
	s_or_b32 s6, s10, 0x20
	v_cmp_ge_u32_e64 s[8:9], v5, s6
	s_bcnt1_i32_b64 s7, s[8:9]
	s_cmp_ge_u32 s7, 16
	s_cselect_b32 s10, s6, s10
	s_or_b32 s6, s10, 0x10
	v_cmp_ge_u32_e64 s[8:9], v5, s6
	s_bcnt1_i32_b64 s7, s[8:9]
	s_cmp_ge_u32 s7, 16
	s_cselect_b32 s10, s6, s10
	s_or_b32 s6, s10, 0x8
	v_cmp_ge_u32_e64 s[8:9], v5, s6
	s_bcnt1_i32_b64 s7, s[8:9]
	s_cmp_ge_u32 s7, 16
	s_cselect_b32 s10, s6, s10
	s_or_b32 s6, s10, 0x4
	v_cmp_ge_u32_e64 s[8:9], v5, s6
	s_bcnt1_i32_b64 s7, s[8:9]
	s_cmp_ge_u32 s7, 16
	s_cselect_b32 s10, s6, s10
	s_or_b32 s6, s10, 0x2
	v_cmp_ge_u32_e64 s[8:9], v5, s6
	s_bcnt1_i32_b64 s7, s[8:9]
	s_cmp_ge_u32 s7, 16
	s_cselect_b32 s10, s6, s10
	s_or_b32 s6, s10, 0x1
	v_cmp_ge_u32_e64 s[8:9], v5, s6
	s_bcnt1_i32_b64 s7, s[8:9]
	s_cmp_ge_u32 s7, 16
	s_cselect_b32 s10, s6, s10
	v_cmp_gt_u32_e64 s[8:9], v5, s10
	v_cmp_eq_u32_e64 vcc, v5, s10
	s_bcnt1_i32_b64 s7, s[8:9]
	s_sub_u32 s7, 16, s7
	v_mbcnt_lo_u32_b32 v6, vcc_lo, 0
	v_mbcnt_hi_u32_b32 v6, vcc_hi, v6
	v_cmp_gt_u32_e64 s[6:7], s7, v6
	s_and_b64 vcc, vcc, s[6:7]
	s_or_b64 s[8:9], s[8:9], vcc
.LBB0_2247:
	s_nop 0
	s_and_saveexec_b64 s[6:7], s[2:3]
	s_cbranch_execz .LBB0_2144
	s_lshl_b32 s10, s31, 3
	v_mov_b32_e32 v4, s10
	v_mov_b64_e32 v[6:7], s[8:9]
	global_store_dwordx2 v4, v[6:7], s[34:35] offset:56
	s_branch .LBB0_2144
